# SSM pass 1: 4th chunk folded into the chunk loop (next-chunk loads skipped on the last trip), carried end state stored directly; peeled chunk removed
# speedup vs baseline: 1.0110x; 1.0024x over previous
; template <bool PASS2>
; __device__ __forceinline__ void ssm_phase(const Params& p, const Frame& F0) {
;     ...
;         bf16x8 uf[4], ufn[4]; u32x2 uw[8], uwn[8];
;         SSM_LOAD_U(uf, uw, 0)
;         for (int cc = 0; cc < nch; ++cc) {
;             asm volatile("" ::: "memory");
;             const bool samp = (cc == 4);
;             const int row0 = SSM_ROW0(cc), nsub = SSM_NSUB(cc), js = jsamp;
;             if (samp) {
; #pragma unroll
;                 for (int i = 0; i < 4; ++i) { xs[i] = *(const f32x4*)(p.in[2] + (size_t)(js * NG + g) * 64 + 16 * i + 4 * gq); xs[i + 4] = *(const f32x4*)(p.in[3] + (size_t)(js * NG + g) * 64 + 16 * i + 4 * gq); } }
;             if (cc + 1 < nch) SSM_LOAD_U(ufn, uwn, cc + 1)
;             unsigned hw[4][4];
; #pragma unroll
;             for (int i = 0; i < 4; ++i) {
;                 __builtin_amdgcn_sched_barrier(0);
;                 f32x4 Er = (f32x4){0.f, 0.f, 0.f, 0.f}, Ei = Er;
; #pragma unroll
;                 for (int ks = 0; ks < 4; ++ks) { Er = __builtin_amdgcn_mfma_f32_16x16x32_bf16(frag[(i * 4 + ks) * 64], uf[ks], Er, 0, 0, 0);
;                                                  Ei = __builtin_amdgcn_mfma_f32_16x16x32_bf16(frag[((i + 4) * 4 + ks) * 64], uf[ks], Ei, 0, 0, 0); }
;                 const f32x4 ma = m1t[8 * i], mb = m1t[8 * i + 1];
;                 float mr[4] = {ma[0], ma[2], mb[0], mb[2]}, mi[4] = {ma[1], ma[3], mb[1], mb[3]};
;                 float hr[4], hi[4];
; #pragma unroll
;                 for (int r = 0; r < 4; ++r) { hr[r] = dppf<DPP_ROR(1)>(xs[i][r]); hi[r] = dppf<DPP_ROR(1)>(xs[i + 4][r]);
;                     if (j == 0) { Er[r] += mr[r] * hr[r] - mi[r] * hi[r]; Ei[r] += mr[r] * hi[r] + mi[r] * hr[r]; } }
.LBB0_527:
	s_waitcnt vmcnt(0)
	v_mov_b64_e32 v[18:19], v[2:3]
	v_mov_b64_e32 v[26:27], v[6:7]
	v_mov_b64_e32 v[16:17], v[0:1]
	v_add_u32_e32 v1, s0, v80
	v_mov_b64_e32 v[24:25], v[4:5]
	v_add_u32_e32 v0, 0x80, v1
	v_add_u32_e32 v2, 0x82, v1
	v_add_u32_e32 v4, 0x84, v1
	v_add_u32_e32 v6, 0x86, v1
	v_ashrrev_i32_e32 v1, 31, v0
	v_ashrrev_i32_e32 v3, 31, v2
	v_ashrrev_i32_e32 v5, 31, v4
	v_mov_b64_e32 v[22:23], v[10:11]
	v_ashrrev_i32_e32 v7, 31, v6
	v_lshlrev_b64 v[0:1], 10, v[0:1]
	v_lshlrev_b64 v[2:3], 10, v[2:3]
	v_lshlrev_b64 v[4:5], 10, v[4:5]
	v_mov_b64_e32 v[30:31], v[14:15]
	v_mov_b64_e32 v[20:21], v[8:9]
	v_lshlrev_b64 v[6:7], 10, v[6:7]
	v_lshl_add_u64 v[0:1], v[64:65], 0, v[0:1]
	v_lshl_add_u64 v[2:3], v[64:65], 0, v[2:3]
	v_lshl_add_u64 v[8:9], v[64:65], 0, v[4:5]
	v_mov_b64_e32 v[28:29], v[12:13]
	v_lshl_add_u64 v[32:33], v[64:65], 0, v[6:7]
	s_cmpk_eq_i32 s0, 0x180
	s_cbranch_scc1 .Lp1_noload
	global_load_dwordx4 v[12:15], v[0:1], off
	global_load_dwordx4 v[4:7], v[2:3], off
	s_nop 0
	global_load_dwordx4 v[8:11], v[8:9], off
	s_nop 0
	global_load_dwordx4 v[0:3], v[32:33], off
.Lp1_noload:
	ds_read_b128 v[90:93], v110 offset:2560
	ds_read_b128 v[94:97], v110 offset:2576
	v_mfma_f32_16x16x32_bf16 v[32:35], v[130:133], v[28:31], 0
	v_mfma_f32_16x16x32_bf16 v[32:35], v[134:137], v[24:27], v[32:35]
	v_mfma_f32_16x16x32_bf16 v[82:85], v[194:197], v[28:31], 0
	v_mfma_f32_16x16x32_bf16 v[82:85], v[198:201], v[24:27], v[82:85]
	v_mfma_f32_16x16x32_bf16 v[32:35], v[138:141], v[20:23], v[32:35]
	v_mfma_f32_16x16x32_bf16 v[82:85], v[204:207], v[20:23], v[82:85]
	v_mfma_f32_16x16x32_bf16 v[86:89], v[142:145], v[16:19], v[32:35]
	v_mfma_f32_16x16x32_bf16 v[82:85], v[208:211], v[16:19], v[82:85]
	s_waitcnt lgkmcnt(1)
	s_nop 1
	s_nop 0
	s_nop 1
	s_nop 1
	v_pk_mul_f32 v[98:99], v[92:93], v[82:83]
	v_pk_mul_f32 v[100:101], v[92:93], v[86:87]
	s_waitcnt lgkmcnt(0)
	v_pk_mul_f32 v[102:103], v[96:97], v[84:85]
	v_pk_mul_f32 v[112:113], v[96:97], v[88:89]
	v_pk_fma_f32 v[86:87], v[90:91], v[86:87], v[98:99] neg_lo:[0,0,1] neg_hi:[0,0,1]
	v_pk_fma_f32 v[82:83], v[90:91], v[82:83], v[100:101]
	v_pk_fma_f32 v[88:89], v[94:95], v[88:89], v[102:103] neg_lo:[0,0,1] neg_hi:[0,0,1]
	v_pk_fma_f32 v[84:85], v[94:95], v[84:85], v[112:113]
	ds_read_b128 v[90:93], v109 offset:2048
	ds_read_b128 v[94:97], v109 offset:2064
	v_add_f32_dpp v86, v86, v86 row_shr:1 row_mask:0xf bank_mask:0xf bound_ctrl:1
	v_add_f32_dpp v87, v87, v87 row_shr:1 row_mask:0xf bank_mask:0xf bound_ctrl:1
	v_add_f32_dpp v82, v82, v82 row_shr:1 row_mask:0xf bank_mask:0xf bound_ctrl:1
	v_add_f32_dpp v83, v83, v83 row_shr:1 row_mask:0xf bank_mask:0xf bound_ctrl:1
	v_add_f32_dpp v88, v88, v88 row_shr:1 row_mask:0xf bank_mask:0xf bound_ctrl:1
	v_add_f32_dpp v89, v89, v89 row_shr:1 row_mask:0xf bank_mask:0xf bound_ctrl:1
	v_add_f32_dpp v84, v84, v84 row_shr:1 row_mask:0xf bank_mask:0xf bound_ctrl:1
	v_add_f32_dpp v85, v85, v85 row_shr:1 row_mask:0xf bank_mask:0xf bound_ctrl:1
	v_add_f32_dpp v86, v86, v86 row_shr:2 row_mask:0xf bank_mask:0xf bound_ctrl:1
	v_add_f32_dpp v87, v87, v87 row_shr:2 row_mask:0xf bank_mask:0xf bound_ctrl:1
	v_add_f32_dpp v82, v82, v82 row_shr:2 row_mask:0xf bank_mask:0xf bound_ctrl:1
	v_add_f32_dpp v83, v83, v83 row_shr:2 row_mask:0xf bank_mask:0xf bound_ctrl:1
	v_add_f32_dpp v88, v88, v88 row_shr:2 row_mask:0xf bank_mask:0xf bound_ctrl:1
	v_add_f32_dpp v89, v89, v89 row_shr:2 row_mask:0xf bank_mask:0xf bound_ctrl:1
	v_add_f32_dpp v84, v84, v84 row_shr:2 row_mask:0xf bank_mask:0xf bound_ctrl:1
	v_add_f32_dpp v85, v85, v85 row_shr:2 row_mask:0xf bank_mask:0xf bound_ctrl:1
	v_add_f32_dpp v86, v86, v86 row_shr:4 row_mask:0xf bank_mask:0xf bound_ctrl:1
	v_add_f32_dpp v87, v87, v87 row_shr:4 row_mask:0xf bank_mask:0xf bound_ctrl:1
	v_add_f32_dpp v82, v82, v82 row_shr:4 row_mask:0xf bank_mask:0xf bound_ctrl:1
	v_add_f32_dpp v83, v83, v83 row_shr:4 row_mask:0xf bank_mask:0xf bound_ctrl:1
	v_add_f32_dpp v88, v88, v88 row_shr:4 row_mask:0xf bank_mask:0xf bound_ctrl:1
	v_add_f32_dpp v89, v89, v89 row_shr:4 row_mask:0xf bank_mask:0xf bound_ctrl:1
	v_add_f32_dpp v84, v84, v84 row_shr:4 row_mask:0xf bank_mask:0xf bound_ctrl:1
	v_add_f32_dpp v85, v85, v85 row_shr:4 row_mask:0xf bank_mask:0xf bound_ctrl:1
	v_add_f32_dpp v86, v86, v86 row_shr:8 row_mask:0xf bank_mask:0xf bound_ctrl:1
	v_add_f32_dpp v87, v87, v87 row_shr:8 row_mask:0xf bank_mask:0xf bound_ctrl:1
	v_add_f32_dpp v82, v82, v82 row_shr:8 row_mask:0xf bank_mask:0xf bound_ctrl:1
	v_add_f32_dpp v83, v83, v83 row_shr:8 row_mask:0xf bank_mask:0xf bound_ctrl:1
	v_add_f32_dpp v88, v88, v88 row_shr:8 row_mask:0xf bank_mask:0xf bound_ctrl:1
	v_add_f32_dpp v89, v89, v89 row_shr:8 row_mask:0xf bank_mask:0xf bound_ctrl:1
	v_add_f32_dpp v84, v84, v84 row_shr:8 row_mask:0xf bank_mask:0xf bound_ctrl:1
	v_add_f32_dpp v85, v85, v85 row_shr:8 row_mask:0xf bank_mask:0xf bound_ctrl:1
	s_waitcnt lgkmcnt(0)
	v_pk_fma_f32 v[86:87], v[90:91], v[72:73], v[86:87]
	v_pk_fma_f32 v[82:83], v[90:91], v[70:71], v[82:83]
	v_pk_fma_f32 v[88:89], v[94:95], v[76:77], v[88:89]
	v_pk_fma_f32 v[84:85], v[94:95], v[74:75], v[84:85]
	v_pk_fma_f32 v[86:87], v[92:93], v[70:71], v[86:87] neg_lo:[1,0,0] neg_hi:[1,0,0]
	v_pk_fma_f32 v[88:89], v[96:97], v[74:75], v[88:89] neg_lo:[1,0,0] neg_hi:[1,0,0]
	v_pk_fma_f32 v[70:71], v[92:93], v[72:73], v[82:83]
	v_pk_fma_f32 v[74:75], v[96:97], v[76:77], v[84:85]
	v_mov_b64_e32 v[72:73], v[86:87]
	v_mov_b64_e32 v[76:77], v[88:89]
	ds_read_b128 v[90:93], v110 offset:2688
	ds_read_b128 v[94:97], v110 offset:2704
	v_mfma_f32_16x16x32_bf16 v[32:35], v[146:149], v[28:31], 0
	v_mfma_f32_16x16x32_bf16 v[32:35], v[150:153], v[24:27], v[32:35]
	v_mfma_f32_16x16x32_bf16 v[82:85], v[212:215], v[28:31], 0
	v_mfma_f32_16x16x32_bf16 v[82:85], v[216:219], v[24:27], v[82:85]
	v_mfma_f32_16x16x32_bf16 v[32:35], v[154:157], v[20:23], v[32:35]
	v_mfma_f32_16x16x32_bf16 v[82:85], v[220:223], v[20:23], v[82:85]
	v_mfma_f32_16x16x32_bf16 v[86:89], v[158:161], v[16:19], v[32:35]
	v_mfma_f32_16x16x32_bf16 v[82:85], v[224:227], v[16:19], v[82:85]
	s_waitcnt lgkmcnt(1)
; __device__ __forceinline__ unsigned cvt_pk_bf16(float lo, float hi) { unsigned r; asm("v_cvt_pk_bf16_f32 %0, %1, %2" : "=v"(r) : "v"(lo), "v"(hi)); return r; }
; #define SSM_SCAN_STEP(D, SQ) { _Pragma("unroll") for (int r = 0; r < 4; ++r) { \
;                     const float sr = dppf<DPP_SHR(D)>(Er[r]), si = dppf<DPP_SHR(D)>(Ei[r]); \
;                     Er[r] += mr[r] * sr - mi[r] * si; Ei[r] += mr[r] * si + mi[r] * sr; \
;                     if (SQ) { const float nr = mr[r] * mr[r] - mi[r] * mi[r], ni = 2.f * mr[r] * mi[r]; mr[r] = nr; mi[r] = ni; } } }
; template <bool PASS2>
; __device__ __forceinline__ void ssm_phase(const Params& p, const Frame& F0) {
;     ...
;             for (int i = 0; i < 4; ++i) {
;                 __builtin_amdgcn_sched_barrier(0);
;                 f32x4 Er = (f32x4){0.f, 0.f, 0.f, 0.f}, Ei = Er;
; #pragma unroll
;                 for (int ks = 0; ks < 4; ++ks) { Er = __builtin_amdgcn_mfma_f32_16x16x32_bf16(frag[(i * 4 + ks) * 64], uf[ks], Er, 0, 0, 0);
;                                                  Ei = __builtin_amdgcn_mfma_f32_16x16x32_bf16(frag[((i + 4) * 4 + ks) * 64], uf[ks], Ei, 0, 0, 0); }
;                 const f32x4 ma = m1t[8 * i], mb = m1t[8 * i + 1];
;                 float mr[4] = {ma[0], ma[2], mb[0], mb[2]}, mi[4] = {ma[1], ma[3], mb[1], mb[3]};
;                 float hr[4], hi[4];
; #pragma unroll
;                 for (int r = 0; r < 4; ++r) { hr[r] = dppf<DPP_ROR(1)>(xs[i][r]); hi[r] = dppf<DPP_ROR(1)>(xs[i + 4][r]);
;                     if (j == 0) { Er[r] += mr[r] * hr[r] - mi[r] * hi[r]; Ei[r] += mr[r] * hi[r] + mi[r] * hr[r]; } }
;     ...
;                 SSM_SCAN_STEP(1, 1) SSM_SCAN_STEP(2, 1) SSM_SCAN_STEP(4, 1) SSM_SCAN_STEP(8, 0)
;     ...
;                 if constexpr (PASS2) {
;                     float vr[4], vi[4];
; #pragma unroll
;                     for (int r = 0; r < 4; ++r) { const float pr_ = dppf<DPP_ROR(1)>(Er[r]), pi_ = dppf<DPP_ROR(1)>(Ei[r]); vr[r] = (j == 0) ? hr[r] : pr_; vi[r] = (j == 0) ? hi[r] : pi_; }
;                     hw[i >> 1][2 * (i & 1)] = cvt_pk_bf16(vr[0], vr[1]); hw[i >> 1][2 * (i & 1) + 1] = cvt_pk_bf16(vr[2], vr[3]);
;                     hw[2 + (i >> 1)][2 * (i & 1)] = cvt_pk_bf16(vi[0], vi[1]); hw[2 + (i >> 1)][2 * (i & 1) + 1] = cvt_pk_bf16(vi[2], vi[3]);
;                 }
;                 xs[i] = Er; xs[i + 4] = Ei;
	s_nop 1
	s_nop 0
	s_nop 1
	s_nop 1
	v_pk_mul_f32 v[98:99], v[92:93], v[82:83]
	v_pk_mul_f32 v[100:101], v[92:93], v[86:87]
	s_waitcnt lgkmcnt(0)
	v_pk_mul_f32 v[102:103], v[96:97], v[84:85]
	v_pk_mul_f32 v[112:113], v[96:97], v[88:89]
	v_pk_fma_f32 v[86:87], v[90:91], v[86:87], v[98:99] neg_lo:[0,0,1] neg_hi:[0,0,1]
	v_pk_fma_f32 v[82:83], v[90:91], v[82:83], v[100:101]
	v_pk_fma_f32 v[88:89], v[94:95], v[88:89], v[102:103] neg_lo:[0,0,1] neg_hi:[0,0,1]
	v_pk_fma_f32 v[84:85], v[94:95], v[84:85], v[112:113]
	ds_read_b128 v[90:93], v109 offset:2176
	ds_read_b128 v[94:97], v109 offset:2192
	v_add_f32_dpp v86, v86, v86 row_shr:1 row_mask:0xf bank_mask:0xf bound_ctrl:1
	v_add_f32_dpp v87, v87, v87 row_shr:1 row_mask:0xf bank_mask:0xf bound_ctrl:1
	v_add_f32_dpp v82, v82, v82 row_shr:1 row_mask:0xf bank_mask:0xf bound_ctrl:1
	v_add_f32_dpp v83, v83, v83 row_shr:1 row_mask:0xf bank_mask:0xf bound_ctrl:1
	v_add_f32_dpp v88, v88, v88 row_shr:1 row_mask:0xf bank_mask:0xf bound_ctrl:1
	v_add_f32_dpp v89, v89, v89 row_shr:1 row_mask:0xf bank_mask:0xf bound_ctrl:1
	v_add_f32_dpp v84, v84, v84 row_shr:1 row_mask:0xf bank_mask:0xf bound_ctrl:1
	v_add_f32_dpp v85, v85, v85 row_shr:1 row_mask:0xf bank_mask:0xf bound_ctrl:1
	v_add_f32_dpp v86, v86, v86 row_shr:2 row_mask:0xf bank_mask:0xf bound_ctrl:1
	v_add_f32_dpp v87, v87, v87 row_shr:2 row_mask:0xf bank_mask:0xf bound_ctrl:1
	v_add_f32_dpp v82, v82, v82 row_shr:2 row_mask:0xf bank_mask:0xf bound_ctrl:1
	v_add_f32_dpp v83, v83, v83 row_shr:2 row_mask:0xf bank_mask:0xf bound_ctrl:1
	v_add_f32_dpp v88, v88, v88 row_shr:2 row_mask:0xf bank_mask:0xf bound_ctrl:1
	v_add_f32_dpp v89, v89, v89 row_shr:2 row_mask:0xf bank_mask:0xf bound_ctrl:1
	v_add_f32_dpp v84, v84, v84 row_shr:2 row_mask:0xf bank_mask:0xf bound_ctrl:1
	v_add_f32_dpp v85, v85, v85 row_shr:2 row_mask:0xf bank_mask:0xf bound_ctrl:1
	v_add_f32_dpp v86, v86, v86 row_shr:4 row_mask:0xf bank_mask:0xf bound_ctrl:1
	v_add_f32_dpp v87, v87, v87 row_shr:4 row_mask:0xf bank_mask:0xf bound_ctrl:1
	v_add_f32_dpp v82, v82, v82 row_shr:4 row_mask:0xf bank_mask:0xf bound_ctrl:1
	v_add_f32_dpp v83, v83, v83 row_shr:4 row_mask:0xf bank_mask:0xf bound_ctrl:1
	v_add_f32_dpp v88, v88, v88 row_shr:4 row_mask:0xf bank_mask:0xf bound_ctrl:1
	v_add_f32_dpp v89, v89, v89 row_shr:4 row_mask:0xf bank_mask:0xf bound_ctrl:1
	v_add_f32_dpp v84, v84, v84 row_shr:4 row_mask:0xf bank_mask:0xf bound_ctrl:1
	v_add_f32_dpp v85, v85, v85 row_shr:4 row_mask:0xf bank_mask:0xf bound_ctrl:1
	v_add_f32_dpp v86, v86, v86 row_shr:8 row_mask:0xf bank_mask:0xf bound_ctrl:1
	v_add_f32_dpp v87, v87, v87 row_shr:8 row_mask:0xf bank_mask:0xf bound_ctrl:1
	v_add_f32_dpp v82, v82, v82 row_shr:8 row_mask:0xf bank_mask:0xf bound_ctrl:1
	v_add_f32_dpp v83, v83, v83 row_shr:8 row_mask:0xf bank_mask:0xf bound_ctrl:1
	v_add_f32_dpp v88, v88, v88 row_shr:8 row_mask:0xf bank_mask:0xf bound_ctrl:1
	v_add_f32_dpp v89, v89, v89 row_shr:8 row_mask:0xf bank_mask:0xf bound_ctrl:1
	v_add_f32_dpp v84, v84, v84 row_shr:8 row_mask:0xf bank_mask:0xf bound_ctrl:1
	v_add_f32_dpp v85, v85, v85 row_shr:8 row_mask:0xf bank_mask:0xf bound_ctrl:1
	s_waitcnt lgkmcnt(0)
	v_pk_fma_f32 v[86:87], v[90:91], v[62:63], v[86:87]
	v_pk_fma_f32 v[82:83], v[90:91], v[60:61], v[82:83]
	v_pk_fma_f32 v[88:89], v[94:95], v[68:69], v[88:89]
	v_pk_fma_f32 v[84:85], v[94:95], v[66:67], v[84:85]
	v_pk_fma_f32 v[86:87], v[92:93], v[60:61], v[86:87] neg_lo:[1,0,0] neg_hi:[1,0,0]
	v_pk_fma_f32 v[88:89], v[96:97], v[66:67], v[88:89] neg_lo:[1,0,0] neg_hi:[1,0,0]
	v_pk_fma_f32 v[60:61], v[92:93], v[62:63], v[82:83]
	v_pk_fma_f32 v[66:67], v[96:97], v[68:69], v[84:85]
	v_mov_b64_e32 v[62:63], v[86:87]
	v_mov_b64_e32 v[68:69], v[88:89]
	ds_read_b128 v[90:93], v110 offset:2816
	ds_read_b128 v[94:97], v110 offset:2832
	v_mfma_f32_16x16x32_bf16 v[32:35], v[162:165], v[28:31], 0
	v_mfma_f32_16x16x32_bf16 v[32:35], v[166:169], v[24:27], v[32:35]
	v_mfma_f32_16x16x32_bf16 v[82:85], v[228:231], v[28:31], 0
	v_mfma_f32_16x16x32_bf16 v[82:85], v[232:235], v[24:27], v[82:85]
	v_mfma_f32_16x16x32_bf16 v[32:35], v[170:173], v[20:23], v[32:35]
	v_mfma_f32_16x16x32_bf16 v[82:85], v[236:239], v[20:23], v[82:85]
	v_mfma_f32_16x16x32_bf16 v[86:89], v[174:177], v[16:19], v[32:35]
	v_mfma_f32_16x16x32_bf16 v[82:85], v[240:243], v[16:19], v[82:85]
	s_waitcnt lgkmcnt(1)
	s_nop 1
	s_nop 0
	s_nop 1
	s_nop 1
	v_pk_mul_f32 v[98:99], v[92:93], v[82:83]
	v_pk_mul_f32 v[100:101], v[92:93], v[86:87]
	s_waitcnt lgkmcnt(0)
; __device__ __forceinline__ unsigned cvt_pk_bf16(float lo, float hi) { unsigned r; asm("v_cvt_pk_bf16_f32 %0, %1, %2" : "=v"(r) : "v"(lo), "v"(hi)); return r; }
; #define SSM_SCAN_STEP(D, SQ) { _Pragma("unroll") for (int r = 0; r < 4; ++r) { \
;                     const float sr = dppf<DPP_SHR(D)>(Er[r]), si = dppf<DPP_SHR(D)>(Ei[r]); \
;                     Er[r] += mr[r] * sr - mi[r] * si; Ei[r] += mr[r] * si + mi[r] * sr; \
;                     if (SQ) { const float nr = mr[r] * mr[r] - mi[r] * mi[r], ni = 2.f * mr[r] * mi[r]; mr[r] = nr; mi[r] = ni; } } }
; template <bool PASS2>
; __device__ __forceinline__ void ssm_phase(const Params& p, const Frame& F0) {
;     ...
;             for (int i = 0; i < 4; ++i) {
;                 __builtin_amdgcn_sched_barrier(0);
;                 f32x4 Er = (f32x4){0.f, 0.f, 0.f, 0.f}, Ei = Er;
; #pragma unroll
;                 for (int ks = 0; ks < 4; ++ks) { Er = __builtin_amdgcn_mfma_f32_16x16x32_bf16(frag[(i * 4 + ks) * 64], uf[ks], Er, 0, 0, 0);
;                                                  Ei = __builtin_amdgcn_mfma_f32_16x16x32_bf16(frag[((i + 4) * 4 + ks) * 64], uf[ks], Ei, 0, 0, 0); }
;                 const f32x4 ma = m1t[8 * i], mb = m1t[8 * i + 1];
;                 float mr[4] = {ma[0], ma[2], mb[0], mb[2]}, mi[4] = {ma[1], ma[3], mb[1], mb[3]};
;                 float hr[4], hi[4];
; #pragma unroll
;                 for (int r = 0; r < 4; ++r) { hr[r] = dppf<DPP_ROR(1)>(xs[i][r]); hi[r] = dppf<DPP_ROR(1)>(xs[i + 4][r]);
;                     if (j == 0) { Er[r] += mr[r] * hr[r] - mi[r] * hi[r]; Ei[r] += mr[r] * hi[r] + mi[r] * hr[r]; } }
;     ...
;                 SSM_SCAN_STEP(1, 1) SSM_SCAN_STEP(2, 1) SSM_SCAN_STEP(4, 1) SSM_SCAN_STEP(8, 0)
;     ...
;                 if constexpr (PASS2) {
;                     float vr[4], vi[4];
; #pragma unroll
;                     for (int r = 0; r < 4; ++r) { const float pr_ = dppf<DPP_ROR(1)>(Er[r]), pi_ = dppf<DPP_ROR(1)>(Ei[r]); vr[r] = (j == 0) ? hr[r] : pr_; vi[r] = (j == 0) ? hi[r] : pi_; }
;                     hw[i >> 1][2 * (i & 1)] = cvt_pk_bf16(vr[0], vr[1]); hw[i >> 1][2 * (i & 1) + 1] = cvt_pk_bf16(vr[2], vr[3]);
;                     hw[2 + (i >> 1)][2 * (i & 1)] = cvt_pk_bf16(vi[0], vi[1]); hw[2 + (i >> 1)][2 * (i & 1) + 1] = cvt_pk_bf16(vi[2], vi[3]);
;                 }
;                 xs[i] = Er; xs[i + 4] = Ei;
	v_pk_mul_f32 v[102:103], v[96:97], v[84:85]
	v_pk_mul_f32 v[112:113], v[96:97], v[88:89]
	v_pk_fma_f32 v[86:87], v[90:91], v[86:87], v[98:99] neg_lo:[0,0,1] neg_hi:[0,0,1]
	v_pk_fma_f32 v[82:83], v[90:91], v[82:83], v[100:101]
	v_pk_fma_f32 v[88:89], v[94:95], v[88:89], v[102:103] neg_lo:[0,0,1] neg_hi:[0,0,1]
	v_pk_fma_f32 v[84:85], v[94:95], v[84:85], v[112:113]
	ds_read_b128 v[90:93], v109 offset:2304
	ds_read_b128 v[94:97], v109 offset:2320
	v_add_f32_dpp v86, v86, v86 row_shr:1 row_mask:0xf bank_mask:0xf bound_ctrl:1
	v_add_f32_dpp v87, v87, v87 row_shr:1 row_mask:0xf bank_mask:0xf bound_ctrl:1
	v_add_f32_dpp v82, v82, v82 row_shr:1 row_mask:0xf bank_mask:0xf bound_ctrl:1
	v_add_f32_dpp v83, v83, v83 row_shr:1 row_mask:0xf bank_mask:0xf bound_ctrl:1
	v_add_f32_dpp v88, v88, v88 row_shr:1 row_mask:0xf bank_mask:0xf bound_ctrl:1
	v_add_f32_dpp v89, v89, v89 row_shr:1 row_mask:0xf bank_mask:0xf bound_ctrl:1
	v_add_f32_dpp v84, v84, v84 row_shr:1 row_mask:0xf bank_mask:0xf bound_ctrl:1
	v_add_f32_dpp v85, v85, v85 row_shr:1 row_mask:0xf bank_mask:0xf bound_ctrl:1
	v_add_f32_dpp v86, v86, v86 row_shr:2 row_mask:0xf bank_mask:0xf bound_ctrl:1
	v_add_f32_dpp v87, v87, v87 row_shr:2 row_mask:0xf bank_mask:0xf bound_ctrl:1
	v_add_f32_dpp v82, v82, v82 row_shr:2 row_mask:0xf bank_mask:0xf bound_ctrl:1
	v_add_f32_dpp v83, v83, v83 row_shr:2 row_mask:0xf bank_mask:0xf bound_ctrl:1
	v_add_f32_dpp v88, v88, v88 row_shr:2 row_mask:0xf bank_mask:0xf bound_ctrl:1
	v_add_f32_dpp v89, v89, v89 row_shr:2 row_mask:0xf bank_mask:0xf bound_ctrl:1
	v_add_f32_dpp v84, v84, v84 row_shr:2 row_mask:0xf bank_mask:0xf bound_ctrl:1
	v_add_f32_dpp v85, v85, v85 row_shr:2 row_mask:0xf bank_mask:0xf bound_ctrl:1
	v_add_f32_dpp v86, v86, v86 row_shr:4 row_mask:0xf bank_mask:0xf bound_ctrl:1
	v_add_f32_dpp v87, v87, v87 row_shr:4 row_mask:0xf bank_mask:0xf bound_ctrl:1
	v_add_f32_dpp v82, v82, v82 row_shr:4 row_mask:0xf bank_mask:0xf bound_ctrl:1
	v_add_f32_dpp v83, v83, v83 row_shr:4 row_mask:0xf bank_mask:0xf bound_ctrl:1
	v_add_f32_dpp v88, v88, v88 row_shr:4 row_mask:0xf bank_mask:0xf bound_ctrl:1
	v_add_f32_dpp v89, v89, v89 row_shr:4 row_mask:0xf bank_mask:0xf bound_ctrl:1
	v_add_f32_dpp v84, v84, v84 row_shr:4 row_mask:0xf bank_mask:0xf bound_ctrl:1
	v_add_f32_dpp v85, v85, v85 row_shr:4 row_mask:0xf bank_mask:0xf bound_ctrl:1
	v_add_f32_dpp v86, v86, v86 row_shr:8 row_mask:0xf bank_mask:0xf bound_ctrl:1
	v_add_f32_dpp v87, v87, v87 row_shr:8 row_mask:0xf bank_mask:0xf bound_ctrl:1
	v_add_f32_dpp v82, v82, v82 row_shr:8 row_mask:0xf bank_mask:0xf bound_ctrl:1
	v_add_f32_dpp v83, v83, v83 row_shr:8 row_mask:0xf bank_mask:0xf bound_ctrl:1
	v_add_f32_dpp v88, v88, v88 row_shr:8 row_mask:0xf bank_mask:0xf bound_ctrl:1
	v_add_f32_dpp v89, v89, v89 row_shr:8 row_mask:0xf bank_mask:0xf bound_ctrl:1
	v_add_f32_dpp v84, v84, v84 row_shr:8 row_mask:0xf bank_mask:0xf bound_ctrl:1
	v_add_f32_dpp v85, v85, v85 row_shr:8 row_mask:0xf bank_mask:0xf bound_ctrl:1
	s_waitcnt lgkmcnt(0)
	v_pk_fma_f32 v[86:87], v[90:91], v[54:55], v[86:87]
	v_pk_fma_f32 v[82:83], v[90:91], v[52:53], v[82:83]
	v_pk_fma_f32 v[88:89], v[94:95], v[58:59], v[88:89]
	v_pk_fma_f32 v[84:85], v[94:95], v[56:57], v[84:85]
	v_pk_fma_f32 v[86:87], v[92:93], v[52:53], v[86:87] neg_lo:[1,0,0] neg_hi:[1,0,0]
	v_pk_fma_f32 v[88:89], v[96:97], v[56:57], v[88:89] neg_lo:[1,0,0] neg_hi:[1,0,0]
	v_pk_fma_f32 v[52:53], v[92:93], v[54:55], v[82:83]
	v_pk_fma_f32 v[56:57], v[96:97], v[58:59], v[84:85]
	v_mov_b64_e32 v[54:55], v[86:87]
	v_mov_b64_e32 v[58:59], v[88:89]
	ds_read_b128 v[90:93], v110 offset:2944
	ds_read_b128 v[94:97], v110 offset:2960
	v_mfma_f32_16x16x32_bf16 v[32:35], v[178:181], v[28:31], 0
	v_mfma_f32_16x16x32_bf16 v[28:31], v[244:247], v[28:31], 0
	v_mfma_f32_16x16x32_bf16 v[32:35], v[182:185], v[24:27], v[32:35]
	v_mfma_f32_16x16x32_bf16 v[24:27], v[248:251], v[24:27], v[28:31]
	v_mfma_f32_16x16x32_bf16 v[28:31], v[186:189], v[20:23], v[32:35]
	v_mfma_f32_16x16x32_bf16 v[20:23], v[114:117], v[20:23], v[24:27]
	s_nop 0
	s_nop 0
	v_mfma_f32_16x16x32_bf16 v[24:27], v[190:193], v[16:19], v[28:31]
	v_mfma_f32_16x16x32_bf16 v[20:23], v[118:121], v[16:19], v[20:23]
	s_waitcnt lgkmcnt(1)
	s_nop 2
	s_nop 3
	v_pk_mul_f32 v[98:99], v[92:93], v[20:21]
	s_nop 1
	v_pk_mul_f32 v[100:101], v[92:93], v[24:25]
	s_waitcnt lgkmcnt(0)
; __device__ __forceinline__ unsigned cvt_pk_bf16(float lo, float hi) { unsigned r; asm("v_cvt_pk_bf16_f32 %0, %1, %2" : "=v"(r) : "v"(lo), "v"(hi)); return r; }
; template <bool PASS2>
; __device__ __forceinline__ void ssm_phase(const Params& p, const Frame& F0) {
;     ...
;             for (int i = 0; i < 4; ++i) {
;                 __builtin_amdgcn_sched_barrier(0);
;                 f32x4 Er = (f32x4){0.f, 0.f, 0.f, 0.f}, Ei = Er;
; #pragma unroll
;                 for (int ks = 0; ks < 4; ++ks) { Er = __builtin_amdgcn_mfma_f32_16x16x32_bf16(frag[(i * 4 + ks) * 64], uf[ks], Er, 0, 0, 0);
;                                                  Ei = __builtin_amdgcn_mfma_f32_16x16x32_bf16(frag[((i + 4) * 4 + ks) * 64], uf[ks], Ei, 0, 0, 0); }
;                 const f32x4 ma = m1t[8 * i], mb = m1t[8 * i + 1];
;                 float mr[4] = {ma[0], ma[2], mb[0], mb[2]}, mi[4] = {ma[1], ma[3], mb[1], mb[3]};
;                 float hr[4], hi[4];
; #pragma unroll
;                 for (int r = 0; r < 4; ++r) { hr[r] = dppf<DPP_ROR(1)>(xs[i][r]); hi[r] = dppf<DPP_ROR(1)>(xs[i + 4][r]);
;                     if (j == 0) { Er[r] += mr[r] * hr[r] - mi[r] * hi[r]; Ei[r] += mr[r] * hi[r] + mi[r] * hr[r]; } }
;     ...
;                 SSM_SCAN_STEP(1, 1) SSM_SCAN_STEP(2, 1) SSM_SCAN_STEP(4, 1) SSM_SCAN_STEP(8, 0)
;     ...
;                 if constexpr (PASS2) {
;                     float vr[4], vi[4];
; #pragma unroll
;                     for (int r = 0; r < 4; ++r) { const float pr_ = dppf<DPP_ROR(1)>(Er[r]), pi_ = dppf<DPP_ROR(1)>(Ei[r]); vr[r] = (j == 0) ? hr[r] : pr_; vi[r] = (j == 0) ? hi[r] : pi_; }
;                     hw[i >> 1][2 * (i & 1)] = cvt_pk_bf16(vr[0], vr[1]); hw[i >> 1][2 * (i & 1) + 1] = cvt_pk_bf16(vr[2], vr[3]);
;                     hw[2 + (i >> 1)][2 * (i & 1)] = cvt_pk_bf16(vi[0], vi[1]); hw[2 + (i >> 1)][2 * (i & 1) + 1] = cvt_pk_bf16(vi[2], vi[3]);
;                 }
;                 xs[i] = Er; xs[i + 4] = Ei;
;             }
;     ...
;         if constexpr (!PASS2) { if (j == 15) { float* wb = Wst + (size_t)((g * 2 + b) * 32 + wch) * 128;
; #pragma unroll
;                 for (int i = 0; i < 4; ++i) { *(f32x4*)(wb + 16 * i + 4 * gq) = xs[i]; *(f32x4*)(wb + 64 + 16 * i + 4 * gq) = xs[i + 4]; } } }
	v_pk_mul_f32 v[102:103], v[96:97], v[22:23]
	v_pk_mul_f32 v[112:113], v[96:97], v[26:27]
	v_pk_fma_f32 v[24:25], v[90:91], v[24:25], v[98:99] neg_lo:[0,0,1] neg_hi:[0,0,1]
	v_pk_fma_f32 v[20:21], v[90:91], v[20:21], v[100:101]
	v_pk_fma_f32 v[26:27], v[94:95], v[26:27], v[102:103] neg_lo:[0,0,1] neg_hi:[0,0,1]
	v_pk_fma_f32 v[22:23], v[94:95], v[22:23], v[112:113]
	ds_read_b128 v[90:93], v109 offset:2432
	ds_read_b128 v[94:97], v109 offset:2448
	v_add_f32_dpp v24, v24, v24 row_shr:1 row_mask:0xf bank_mask:0xf bound_ctrl:1
	v_add_f32_dpp v25, v25, v25 row_shr:1 row_mask:0xf bank_mask:0xf bound_ctrl:1
	v_add_f32_dpp v20, v20, v20 row_shr:1 row_mask:0xf bank_mask:0xf bound_ctrl:1
	v_add_f32_dpp v21, v21, v21 row_shr:1 row_mask:0xf bank_mask:0xf bound_ctrl:1
	v_add_f32_dpp v26, v26, v26 row_shr:1 row_mask:0xf bank_mask:0xf bound_ctrl:1
	v_add_f32_dpp v27, v27, v27 row_shr:1 row_mask:0xf bank_mask:0xf bound_ctrl:1
	v_add_f32_dpp v22, v22, v22 row_shr:1 row_mask:0xf bank_mask:0xf bound_ctrl:1
	v_add_f32_dpp v23, v23, v23 row_shr:1 row_mask:0xf bank_mask:0xf bound_ctrl:1
	v_add_f32_dpp v24, v24, v24 row_shr:2 row_mask:0xf bank_mask:0xf bound_ctrl:1
	v_add_f32_dpp v25, v25, v25 row_shr:2 row_mask:0xf bank_mask:0xf bound_ctrl:1
	v_add_f32_dpp v20, v20, v20 row_shr:2 row_mask:0xf bank_mask:0xf bound_ctrl:1
	v_add_f32_dpp v21, v21, v21 row_shr:2 row_mask:0xf bank_mask:0xf bound_ctrl:1
	v_add_f32_dpp v26, v26, v26 row_shr:2 row_mask:0xf bank_mask:0xf bound_ctrl:1
	v_add_f32_dpp v27, v27, v27 row_shr:2 row_mask:0xf bank_mask:0xf bound_ctrl:1
	v_add_f32_dpp v22, v22, v22 row_shr:2 row_mask:0xf bank_mask:0xf bound_ctrl:1
	v_add_f32_dpp v23, v23, v23 row_shr:2 row_mask:0xf bank_mask:0xf bound_ctrl:1
	v_add_f32_dpp v24, v24, v24 row_shr:4 row_mask:0xf bank_mask:0xf bound_ctrl:1
	v_add_f32_dpp v25, v25, v25 row_shr:4 row_mask:0xf bank_mask:0xf bound_ctrl:1
	v_add_f32_dpp v20, v20, v20 row_shr:4 row_mask:0xf bank_mask:0xf bound_ctrl:1
	v_add_f32_dpp v21, v21, v21 row_shr:4 row_mask:0xf bank_mask:0xf bound_ctrl:1
	v_add_f32_dpp v26, v26, v26 row_shr:4 row_mask:0xf bank_mask:0xf bound_ctrl:1
	v_add_f32_dpp v27, v27, v27 row_shr:4 row_mask:0xf bank_mask:0xf bound_ctrl:1
	v_add_f32_dpp v22, v22, v22 row_shr:4 row_mask:0xf bank_mask:0xf bound_ctrl:1
	v_add_f32_dpp v23, v23, v23 row_shr:4 row_mask:0xf bank_mask:0xf bound_ctrl:1
	v_add_f32_dpp v24, v24, v24 row_shr:8 row_mask:0xf bank_mask:0xf bound_ctrl:1
	v_add_f32_dpp v25, v25, v25 row_shr:8 row_mask:0xf bank_mask:0xf bound_ctrl:1
	v_add_f32_dpp v20, v20, v20 row_shr:8 row_mask:0xf bank_mask:0xf bound_ctrl:1
	v_add_f32_dpp v21, v21, v21 row_shr:8 row_mask:0xf bank_mask:0xf bound_ctrl:1
	v_add_f32_dpp v26, v26, v26 row_shr:8 row_mask:0xf bank_mask:0xf bound_ctrl:1
	v_add_f32_dpp v27, v27, v27 row_shr:8 row_mask:0xf bank_mask:0xf bound_ctrl:1
	v_add_f32_dpp v22, v22, v22 row_shr:8 row_mask:0xf bank_mask:0xf bound_ctrl:1
	v_add_f32_dpp v23, v23, v23 row_shr:8 row_mask:0xf bank_mask:0xf bound_ctrl:1
	s_waitcnt lgkmcnt(0)
	v_pk_fma_f32 v[24:25], v[90:91], v[46:47], v[24:25]
	v_pk_fma_f32 v[20:21], v[90:91], v[44:45], v[20:21]
	v_pk_fma_f32 v[26:27], v[94:95], v[50:51], v[26:27]
	v_pk_fma_f32 v[22:23], v[94:95], v[48:49], v[22:23]
	v_pk_fma_f32 v[24:25], v[92:93], v[44:45], v[24:25] neg_lo:[1,0,0] neg_hi:[1,0,0]
	v_pk_fma_f32 v[26:27], v[96:97], v[48:49], v[26:27] neg_lo:[1,0,0] neg_hi:[1,0,0]
	v_pk_fma_f32 v[44:45], v[92:93], v[46:47], v[20:21]
	v_pk_fma_f32 v[48:49], v[96:97], v[50:51], v[22:23]
	v_mov_b64_e32 v[46:47], v[24:25]
	v_mov_b64_e32 v[50:51], v[26:27]
	s_addk_i32 s0, 0x80
	s_cmpk_eq_i32 s0, 0x200
	s_cbranch_scc0 .LBB0_527
	s_and_saveexec_b64 s[0:1], s[8:9]
	s_cbranch_execz .LBB0_520
	s_lshl_b32 s10, s16, 6
	s_lshl_b32 s16, s17, 5
	s_add_i32 s16, s18, s16
	s_add_i32 s16, s16, s10
	s_ashr_i32 s17, s16, 31
	s_lshl_b64 s[16:17], s[16:17], 9
	v_lshl_add_u64 v[8:9], v[40:41], 0, s[16:17]
	global_store_dwordx2 v[8:9], v[72:73], off
	global_store_dwordx2 v[8:9], v[76:77], off offset:8
	global_store_dwordx2 v[8:9], v[70:71], off offset:256
	global_store_dwordx2 v[8:9], v[74:75], off offset:264
	global_store_dwordx2 v[8:9], v[62:63], off offset:64
	global_store_dwordx2 v[8:9], v[68:69], off offset:72
	global_store_dwordx2 v[8:9], v[60:61], off offset:320
	global_store_dwordx2 v[8:9], v[66:67], off offset:328
	global_store_dwordx2 v[8:9], v[54:55], off offset:128
	global_store_dwordx2 v[8:9], v[58:59], off offset:136
	global_store_dwordx2 v[8:9], v[52:53], off offset:384
	global_store_dwordx2 v[8:9], v[56:57], off offset:392
	global_store_dwordx2 v[8:9], v[46:47], off offset:192
	global_store_dwordx2 v[8:9], v[50:51], off offset:200
	global_store_dwordx2 v[8:9], v[44:45], off offset:448
	global_store_dwordx2 v[8:9], v[48:49], off offset:456
	s_branch .LBB0_520
